# prep_rwkv phase A: 32 serialized small loads folded into 5 wide loads issued together
# speedup vs baseline: 1.2730x; 1.0014x over previous
.LBB0_204:
	s_andn2_b64 vcc, exec, s[0:1]
	s_cbranch_vccnz .LBB0_153
	s_waitcnt vmcnt(6)
	v_mov_b32_e32 v0, v128
	s_lshl_b32 s60, s25, 3
	s_waitcnt vmcnt(4)
	v_ashrrev_i32_e32 v11, 5, v0
	v_add_u32_e32 v4, s60, v11
	s_movk_i32 s0, 0x1000
	v_cmp_gt_i32_e32 vcc, s0, v4
	v_readlane_b32 s0, v254, 63
	v_lshlrev_b32_e32 v1, 3, v0
	v_readlane_b32 s1, v255, 0
	v_and_b32_e32 v1, 0xf8, v1
	s_movk_i32 s2, 0x4a00
	v_mov_b64_e32 v[2:3], s[0:1]
	v_add_u32_e32 v7, -1, v4
	v_mad_i64_i32 v[8:9], s[0:1], v4, s2, v[2:3]
	v_mad_i64_i32 v[2:3], s[0:1], v7, s2, v[2:3]
	v_or_b32_e32 v7, 0xe00, v1
	v_lshlrev_b32_e32 v130, 1, v7
	s_waitcnt vmcnt(3)
	v_lshl_add_u64 v[166:167], v[8:9], 0, v[130:131]
	v_lshl_add_u64 v[168:169], v[2:3], 0, v[130:131]
	global_load_dwordx4 v[146:149], v[166:167], off
	global_load_dwordx4 v[150:153], v[168:169], off
	s_mov_b64 s[0:1], 0x4a00
	v_lshlrev_b32_e32 v170, 2, v1
	v_lshl_add_u64 v[168:169], v[166:167], 0, s[0:1]
	v_add_u32_e32 v170, 0x1800, v170
	global_load_dwordx4 v[154:157], v[168:169], off
	global_load_dwordx4 v[158:161], v170, s[46:47]
	global_load_dwordx4 v[162:165], v170, s[46:47] offset:16
	s_waitcnt vmcnt(0)
	v_lshl_add_u64 v[12:13], v[8:9], 0, v[130:131]
	v_and_b32_e32 v12, 0xffff, v146
	v_cndmask_b32_e32 v5, v230, v231, vcc
	v_and_b32_e32 v6, v5, v4
	v_cmp_ne_u32_e64 s[38:39], 0, v6
	v_mov_b32_e32 v14, 0
	v_mov_b32_e32 v13, 0
	s_and_saveexec_b64 s[0:1], s[38:39]
	s_cbranch_execz .LBB0_207
	s_waitcnt vmcnt(3)
	v_lshl_add_u64 v[16:17], v[2:3], 0, v[130:131]
	v_and_b32_e32 v7, 0xffff, v150
	s_waitcnt vmcnt(0)
	v_lshlrev_b32_e32 v13, 16, v7
.LBB0_207:
	s_or_b64 exec, exec, s[0:1]
	v_readlane_b32 s0, v254, 63
	v_readlane_b32 s1, v255, 0
	v_cmp_ne_u32_e64 s[40:41], v6, v5
	v_add_u32_e32 v6, 1, v4
	v_mov_b64_e32 v[4:5], s[0:1]
	s_movk_i32 s0, 0x4a00
	v_mad_i64_i32 v[4:5], s[0:1], v6, s0, v[4:5]
	s_and_saveexec_b64 s[0:1], s[40:41]
	s_cbranch_execz .LBB0_209
	v_lshl_add_u64 v[6:7], v[4:5], 0, v[130:131]
	v_and_b32_e32 v6, 0xffff, v154
	s_waitcnt vmcnt(0)
	v_lshlrev_b32_e32 v14, 16, v6
.LBB0_209:
	s_or_b64 exec, exec, s[0:1]
	v_lshlrev_b32_e32 v130, 2, v1
	v_lshl_add_u64 v[6:7], s[46:47], 0, v[130:131]
	s_waitcnt vmcnt(3)
	v_add_co_u32_e32 v16, vcc, 0x1000, v6
	v_lshrrev_b32_e32 v10, 6, v1
	s_nop 0
	v_addc_co_u32_e32 v17, vcc, 0, v7, vcc
	v_mov_b32_e32 v18, v158
	v_or_b32_e32 v15, 0xe01, v1
	s_movk_i32 s0, 0xe0
	v_and_or_b32 v19, v130, s0, v10
	v_lshlrev_b32_e32 v130, 1, v15
	v_lshl_add_u64 v[16:17], v[8:9], 0, v[130:131]
	v_lshrrev_b32_e32 v15, 16, v146
	s_waitcnt vmcnt(2)
	v_lshlrev_b32_e32 v12, 16, v12
	v_add_f32_e32 v13, v13, v14
	v_fma_f32 v13, v13, 0.5, -v12
	s_movk_i32 s0, 0x80
	v_lshlrev_b32_e32 v58, 2, v11
	v_cmp_gt_u32_e64 s[36:37], s0, v1
	v_lshl_add_u32 v14, v19, 5, v58
	v_mov_b32_e32 v11, 0
	s_waitcnt vmcnt(1)
	v_fmac_f32_e32 v12, v18, v13
	v_add_f32_e32 v13, v12, v12
	v_mul_f32_e32 v13, 0x3fb8aa3b, v13
	v_exp_f32_e32 v13, v13
	s_nop 0
	v_add_f32_e32 v13, 1.0, v13
	v_rcp_f32_e32 v13, v13
	s_nop 0
	v_fma_f32 v13, v13, -2.0, 1.0
	v_cndmask_b32_e64 v12, v12, v13, s[36:37]
	ds_write_b32 v14, v12
	v_mov_b32_e32 v12, 0
	s_and_saveexec_b64 s[0:1], s[38:39]
	s_cbranch_execz .LBB0_211
	v_lshl_add_u64 v[12:13], v[2:3], 0, v[130:131]
	v_lshrrev_b32_e32 v12, 16, v150
	s_waitcnt vmcnt(0)
	v_lshlrev_b32_e32 v12, 16, v12
.LBB0_211:
	s_or_b64 exec, exec, s[0:1]
	s_and_saveexec_b64 s[0:1], s[40:41]
	s_cbranch_execz .LBB0_213
	v_lshl_add_u64 v[16:17], v[4:5], 0, v[130:131]
	v_lshrrev_b32_e32 v11, 16, v154
	s_waitcnt vmcnt(0)
	v_lshlrev_b32_e32 v11, 16, v11
.LBB0_213:
	s_or_b64 exec, exec, s[0:1]
	v_add_co_u32_e32 v14, vcc, 0x1000, v6
	s_waitcnt vmcnt(0)
	v_lshlrev_b32_e32 v13, 16, v15
	v_addc_co_u32_e32 v15, vcc, 0, v7, vcc
	v_mov_b32_e32 v14, v159
	v_add_f32_e32 v11, v12, v11
	v_fma_f32 v11, v11, 0.5, -v13
	v_lshl_or_b32 v12, v1, 2, 4
	s_movk_i32 s0, 0xe4
	v_and_or_b32 v12, v12, s0, v10
	v_lshl_add_u32 v12, v12, 5, v58
	s_waitcnt vmcnt(0)
	v_fmac_f32_e32 v13, v14, v11
	v_add_f32_e32 v11, v13, v13
	v_mul_f32_e32 v11, 0x3fb8aa3b, v11
	v_exp_f32_e32 v11, v11
	s_nop 0
	v_add_f32_e32 v11, 1.0, v11
	v_rcp_f32_e32 v11, v11
	s_nop 0
	v_fma_f32 v11, v11, -2.0, 1.0
	v_cndmask_b32_e64 v11, v13, v11, s[36:37]
	ds_write_b32 v12, v11
	v_or_b32_e32 v11, 0xe02, v1
	v_lshlrev_b32_e32 v130, 1, v11
	v_lshl_add_u64 v[12:13], v[8:9], 0, v[130:131]
	v_and_b32_e32 v11, 0xffff, v147
	v_mov_b32_e32 v12, 0
	v_mov_b32_e32 v13, 0
	s_and_saveexec_b64 s[0:1], s[38:39]
	s_cbranch_execz .LBB0_215
	v_lshl_add_u64 v[14:15], v[2:3], 0, v[130:131]
	v_and_b32_e32 v13, 0xffff, v151
	s_waitcnt vmcnt(0)
	v_lshlrev_b32_e32 v13, 16, v13
.LBB0_215:
	s_or_b64 exec, exec, s[0:1]
	s_and_saveexec_b64 s[0:1], s[40:41]
	s_cbranch_execz .LBB0_217
	v_lshl_add_u64 v[14:15], v[4:5], 0, v[130:131]
	v_and_b32_e32 v12, 0xffff, v155
	s_waitcnt vmcnt(0)
	v_lshlrev_b32_e32 v12, 16, v12
.LBB0_217:
	s_or_b64 exec, exec, s[0:1]
	v_add_co_u32_e32 v14, vcc, 0x1000, v6
	s_waitcnt vmcnt(0)
	v_lshlrev_b32_e32 v11, 16, v11
	v_addc_co_u32_e32 v15, vcc, 0, v7, vcc
	v_mov_b32_e32 v14, v160
	v_add_f32_e32 v12, v13, v12
	v_fma_f32 v12, v12, 0.5, -v11
	s_movk_i32 s0, 0xe8
	s_waitcnt vmcnt(0)
	v_fmac_f32_e32 v11, v14, v12
	v_add_f32_e32 v12, v11, v11
	v_mul_f32_e32 v12, 0x3fb8aa3b, v12
	v_exp_f32_e32 v12, v12
	s_nop 0
	v_add_f32_e32 v12, 1.0, v12
	v_rcp_f32_e32 v12, v12
	s_nop 0
	v_fma_f32 v12, v12, -2.0, 1.0
	v_cndmask_b32_e64 v11, v11, v12, s[36:37]
	v_lshl_or_b32 v12, v1, 2, 8
	v_and_or_b32 v12, v12, s0, v10
	v_lshl_add_u32 v12, v12, 5, v58
	ds_write_b32 v12, v11
	v_or_b32_e32 v11, 0xe03, v1
	v_lshlrev_b32_e32 v130, 1, v11
	v_lshl_add_u64 v[12:13], v[8:9], 0, v[130:131]
	v_lshrrev_b32_e32 v11, 16, v147
	v_mov_b32_e32 v12, 0
	v_mov_b32_e32 v13, 0
	s_and_saveexec_b64 s[0:1], s[38:39]
	s_cbranch_execz .LBB0_219
	v_lshl_add_u64 v[14:15], v[2:3], 0, v[130:131]
	v_lshrrev_b32_e32 v13, 16, v151
	s_waitcnt vmcnt(0)
	v_lshlrev_b32_e32 v13, 16, v13
.LBB0_219:
	s_or_b64 exec, exec, s[0:1]
	s_and_saveexec_b64 s[0:1], s[40:41]
	s_cbranch_execz .LBB0_221
	v_lshl_add_u64 v[14:15], v[4:5], 0, v[130:131]
	v_lshrrev_b32_e32 v12, 16, v155
	s_waitcnt vmcnt(0)
	v_lshlrev_b32_e32 v12, 16, v12
.LBB0_221:
	s_or_b64 exec, exec, s[0:1]
	v_add_co_u32_e32 v14, vcc, 0x1000, v6
	s_waitcnt vmcnt(0)
	v_lshlrev_b32_e32 v11, 16, v11
	v_addc_co_u32_e32 v15, vcc, 0, v7, vcc
	v_mov_b32_e32 v14, v161
	v_add_f32_e32 v12, v13, v12
	v_fma_f32 v12, v12, 0.5, -v11
	s_movk_i32 s0, 0xec
	s_waitcnt vmcnt(0)
	v_fmac_f32_e32 v11, v14, v12
	v_add_f32_e32 v12, v11, v11
	v_mul_f32_e32 v12, 0x3fb8aa3b, v12
	v_exp_f32_e32 v12, v12
	s_nop 0
	v_add_f32_e32 v12, 1.0, v12
	v_rcp_f32_e32 v12, v12
	s_nop 0
	v_fma_f32 v12, v12, -2.0, 1.0
	v_cndmask_b32_e64 v11, v11, v12, s[36:37]
	v_lshl_or_b32 v12, v1, 2, 12
	v_and_or_b32 v12, v12, s0, v10
	v_lshl_add_u32 v12, v12, 5, v58
	ds_write_b32 v12, v11
	v_or_b32_e32 v11, 0xe04, v1
	v_lshlrev_b32_e32 v130, 1, v11
	v_lshl_add_u64 v[12:13], v[8:9], 0, v[130:131]
	v_and_b32_e32 v11, 0xffff, v148
	v_mov_b32_e32 v12, 0
	v_mov_b32_e32 v13, 0
	s_and_saveexec_b64 s[0:1], s[38:39]
	s_cbranch_execz .LBB0_223
	v_lshl_add_u64 v[14:15], v[2:3], 0, v[130:131]
	v_and_b32_e32 v13, 0xffff, v152
	s_waitcnt vmcnt(0)
	v_lshlrev_b32_e32 v13, 16, v13
.LBB0_223:
	s_or_b64 exec, exec, s[0:1]
	s_and_saveexec_b64 s[0:1], s[40:41]
	s_cbranch_execz .LBB0_225
	v_lshl_add_u64 v[14:15], v[4:5], 0, v[130:131]
	v_and_b32_e32 v12, 0xffff, v156
	s_waitcnt vmcnt(0)
	v_lshlrev_b32_e32 v12, 16, v12
.LBB0_225:
	s_or_b64 exec, exec, s[0:1]
	v_add_co_u32_e32 v14, vcc, 0x1000, v6
	s_waitcnt vmcnt(0)
	v_lshlrev_b32_e32 v11, 16, v11
	v_addc_co_u32_e32 v15, vcc, 0, v7, vcc
	v_mov_b32_e32 v14, v162
	v_add_f32_e32 v12, v13, v12
	v_fma_f32 v12, v12, 0.5, -v11
	s_movk_i32 s0, 0xf0
	s_waitcnt vmcnt(0)
	v_fmac_f32_e32 v11, v14, v12
	v_add_f32_e32 v12, v11, v11
	v_mul_f32_e32 v12, 0x3fb8aa3b, v12
	v_exp_f32_e32 v12, v12
	s_nop 0
	v_add_f32_e32 v12, 1.0, v12
	v_rcp_f32_e32 v12, v12
	s_nop 0
	v_fma_f32 v12, v12, -2.0, 1.0
	v_cndmask_b32_e64 v11, v11, v12, s[36:37]
	v_lshl_or_b32 v12, v1, 2, 16
	v_and_or_b32 v12, v12, s0, v10
	v_lshl_add_u32 v12, v12, 5, v58
	ds_write_b32 v12, v11
	v_or_b32_e32 v11, 0xe05, v1
	v_lshlrev_b32_e32 v130, 1, v11
	v_lshl_add_u64 v[12:13], v[8:9], 0, v[130:131]
	v_lshrrev_b32_e32 v11, 16, v148
	v_mov_b32_e32 v12, 0
	v_mov_b32_e32 v13, 0
	s_and_saveexec_b64 s[0:1], s[38:39]
	s_cbranch_execz .LBB0_227
	v_lshl_add_u64 v[14:15], v[2:3], 0, v[130:131]
	v_lshrrev_b32_e32 v13, 16, v152
	s_waitcnt vmcnt(0)
	v_lshlrev_b32_e32 v13, 16, v13
.LBB0_227:
	s_or_b64 exec, exec, s[0:1]
	s_and_saveexec_b64 s[0:1], s[40:41]
	s_cbranch_execz .LBB0_229
	v_lshl_add_u64 v[14:15], v[4:5], 0, v[130:131]
	v_lshrrev_b32_e32 v12, 16, v156
	s_waitcnt vmcnt(0)
	v_lshlrev_b32_e32 v12, 16, v12
.LBB0_229:
	s_or_b64 exec, exec, s[0:1]
	v_add_co_u32_e32 v14, vcc, 0x1000, v6
	s_waitcnt vmcnt(0)
	v_lshlrev_b32_e32 v11, 16, v11
	v_addc_co_u32_e32 v15, vcc, 0, v7, vcc
	v_mov_b32_e32 v14, v163
	v_add_f32_e32 v12, v13, v12
	v_fma_f32 v12, v12, 0.5, -v11
	s_movk_i32 s0, 0xf4
	s_waitcnt vmcnt(0)
	v_fmac_f32_e32 v11, v14, v12
	v_add_f32_e32 v12, v11, v11
	v_mul_f32_e32 v12, 0x3fb8aa3b, v12
	v_exp_f32_e32 v12, v12
	s_nop 0
	v_add_f32_e32 v12, 1.0, v12
	v_rcp_f32_e32 v12, v12
	s_nop 0
	v_fma_f32 v12, v12, -2.0, 1.0
	v_cndmask_b32_e64 v11, v11, v12, s[36:37]
	v_lshl_or_b32 v12, v1, 2, 20
	v_and_or_b32 v12, v12, s0, v10
	v_lshl_add_u32 v12, v12, 5, v58
	ds_write_b32 v12, v11
	v_or_b32_e32 v11, 0xe06, v1
	v_lshlrev_b32_e32 v130, 1, v11
	v_lshl_add_u64 v[12:13], v[8:9], 0, v[130:131]
	v_and_b32_e32 v11, 0xffff, v149
	v_mov_b32_e32 v12, 0
	v_mov_b32_e32 v13, 0
	s_and_saveexec_b64 s[0:1], s[38:39]
	s_cbranch_execz .LBB0_231
	v_lshl_add_u64 v[14:15], v[2:3], 0, v[130:131]
	v_and_b32_e32 v13, 0xffff, v153
	s_waitcnt vmcnt(0)
	v_lshlrev_b32_e32 v13, 16, v13
.LBB0_231:
	s_or_b64 exec, exec, s[0:1]
	s_and_saveexec_b64 s[0:1], s[40:41]
	s_cbranch_execz .LBB0_233
	v_lshl_add_u64 v[14:15], v[4:5], 0, v[130:131]
	v_and_b32_e32 v12, 0xffff, v157
	s_waitcnt vmcnt(0)
	v_lshlrev_b32_e32 v12, 16, v12
.LBB0_233:
	s_or_b64 exec, exec, s[0:1]
	v_add_co_u32_e32 v14, vcc, 0x1000, v6
	s_waitcnt vmcnt(0)
	v_lshlrev_b32_e32 v11, 16, v11
	v_addc_co_u32_e32 v15, vcc, 0, v7, vcc
	v_mov_b32_e32 v14, v164
	v_add_f32_e32 v12, v13, v12
	v_fma_f32 v12, v12, 0.5, -v11
	s_movk_i32 s0, 0xf8
	s_waitcnt vmcnt(0)
	v_fmac_f32_e32 v11, v14, v12
	v_add_f32_e32 v12, v11, v11
	v_mul_f32_e32 v12, 0x3fb8aa3b, v12
	v_exp_f32_e32 v12, v12
	s_nop 0
	v_add_f32_e32 v12, 1.0, v12
	v_rcp_f32_e32 v12, v12
	s_nop 0
	v_fma_f32 v12, v12, -2.0, 1.0
	v_cndmask_b32_e64 v11, v11, v12, s[36:37]
	v_lshl_or_b32 v12, v1, 2, 24
	v_and_or_b32 v12, v12, s0, v10
	v_lshl_add_u32 v12, v12, 5, v58
	ds_write_b32 v12, v11
	v_or_b32_e32 v11, 0xe07, v1
	v_lshlrev_b32_e32 v130, 1, v11
	v_lshl_add_u64 v[8:9], v[8:9], 0, v[130:131]
	v_lshrrev_b32_e32 v8, 16, v149
	v_mov_b32_e32 v9, 0
	v_mov_b32_e32 v11, 0
	s_and_saveexec_b64 s[0:1], s[38:39]
	s_cbranch_execz .LBB0_235
	v_lshl_add_u64 v[2:3], v[2:3], 0, v[130:131]
	v_lshrrev_b32_e32 v2, 16, v153
	s_waitcnt vmcnt(0)
	v_lshlrev_b32_e32 v11, 16, v2
.LBB0_235:
	s_or_b64 exec, exec, s[0:1]
	s_and_saveexec_b64 s[0:1], s[40:41]
	s_cbranch_execz .LBB0_237
	v_lshl_add_u64 v[2:3], v[4:5], 0, v[130:131]
	v_lshrrev_b32_e32 v2, 16, v157
	s_waitcnt vmcnt(0)
	v_lshlrev_b32_e32 v9, 16, v2
.LBB0_237:
	s_or_b64 exec, exec, s[0:1]
	v_add_co_u32_e32 v2, vcc, 0x1000, v6
	s_waitcnt vmcnt(0)
	v_lshlrev_b32_e32 v62, 16, v8
	v_addc_co_u32_e32 v3, vcc, 0, v7, vcc
	v_mov_b32_e32 v16, v165
	v_add_f32_e32 v3, v11, v9
	v_fma_f32 v8, v3, 0.5, -v62
	v_lshl_or_b32 v4, v1, 2, 28
	v_ashrrev_i32_e32 v1, 31, v0
	s_movk_i32 s28, 0xfc
	v_readlane_b32 s2, v255, 40
	v_and_or_b32 v9, v4, s28, v10
	v_lshlrev_b64 v[60:61], 2, v[0:1]
	v_readlane_b32 s3, v255, 41
	v_lshl_add_u32 v9, v9, 5, v58
	v_mov_b32_e32 v2, 0
	s_mov_b32 s0, 0
	s_movk_i32 s1, 0x600
	s_mov_b64 s[26:27], 0
	v_mov_b32_e32 v3, v2
	v_mov_b32_e32 v10, v2
	v_mov_b32_e32 v11, v2
	v_mov_b32_e32 v18, v2
	v_mov_b32_e32 v19, v2
	v_mov_b32_e32 v26, v2
	v_mov_b32_e32 v27, v2
	v_mov_b32_e32 v6, v2
	v_mov_b32_e32 v7, v2
	v_mov_b32_e32 v14, v2
	v_mov_b32_e32 v15, v2
	v_mov_b32_e32 v22, v2
	v_mov_b32_e32 v23, v2
	v_mov_b32_e32 v30, v2
	v_mov_b32_e32 v31, v2
	v_mov_b32_e32 v4, v2
	v_mov_b32_e32 v5, v2
	v_mov_b32_e32 v12, v2
	v_mov_b32_e32 v13, v2
	v_mov_b32_e32 v20, v2
	v_mov_b32_e32 v21, v2
	v_mov_b32_e32 v28, v2
	v_mov_b32_e32 v29, v2
	v_mov_b32_e32 v40, v2
	v_mov_b32_e32 v41, v2
	v_mov_b32_e32 v48, v2
	v_mov_b32_e32 v49, v2
	v_mov_b32_e32 v56, v2
	v_mov_b32_e32 v57, v2
	v_mov_b32_e32 v70, v2
	v_mov_b32_e32 v71, v2
	v_mov_b32_e32 v34, v2
	v_mov_b32_e32 v35, v2
	v_mov_b32_e32 v42, v2
	v_mov_b32_e32 v43, v2
	v_mov_b32_e32 v50, v2
	v_mov_b32_e32 v51, v2
	v_mov_b32_e32 v64, v2
	v_mov_b32_e32 v65, v2
	v_mov_b32_e32 v38, v2
	v_mov_b32_e32 v39, v2
	v_mov_b32_e32 v46, v2
	v_mov_b32_e32 v47, v2
	v_mov_b32_e32 v54, v2
	v_mov_b32_e32 v55, v2
	v_mov_b32_e32 v68, v2
	v_mov_b32_e32 v69, v2
	v_mov_b32_e32 v36, v2
	v_mov_b32_e32 v37, v2
	v_mov_b32_e32 v44, v2
	v_mov_b32_e32 v45, v2
	v_mov_b32_e32 v52, v2
	v_mov_b32_e32 v53, v2
	v_mov_b32_e32 v66, v2
	v_mov_b32_e32 v67, v2
	v_mov_b32_e32 v32, v2
	v_mov_b32_e32 v33, v2
	v_mov_b32_e32 v24, v2
	v_mov_b32_e32 v25, v2
	v_mov_b32_e32 v17, v2
	s_waitcnt vmcnt(0)
	v_fmac_f32_e32 v62, v16, v8
	v_add_f32_e32 v8, v62, v62
	v_mul_f32_e32 v8, 0x3fb8aa3b, v8
	v_exp_f32_e32 v59, v8
	v_mov_b32_e32 v16, v2
	v_mov_b32_e32 v8, v2
	v_add_f32_e32 v59, 1.0, v59
	v_rcp_f32_e32 v63, v59
	v_lshl_add_u64 v[58:59], s[2:3], 0, v[60:61]
	v_readlane_b32 s2, v255, 42
	v_readlane_b32 s3, v255, 43
	v_fma_f32 v63, v63, -2.0, 1.0
	v_cndmask_b32_e64 v62, v62, v63, s[36:37]
	v_lshl_add_u64 v[60:61], s[2:3], 0, v[60:61]
	ds_write_b32 v9, v62
	v_mov_b32_e32 v9, v2
	s_movk_i32 s2, 0x1000
	s_mov_b32 s3, 0x21000
	s_waitcnt lgkmcnt(0)
	s_barrier
